# KS=4 skinny rewrites with s_nop padding at once-per-phase spots so the three GEMM loop heads keep the previous version's byte phase (mod 64)
# speedup vs baseline: 1.0057x; 1.0057x over previous
.LBB0_98:
	s_nop 0
	s_nop 0
	s_nop 0
	s_nop 0
	s_nop 0
	s_nop 0
	s_nop 0
	s_nop 0
	s_nop 0
	s_nop 0
	s_nop 0
	s_nop 0
	s_nop 0
	s_branch .LBB0_144

.LBB0_280:
	s_nop 0
	s_nop 0
	s_nop 0
	s_nop 0
	s_nop 0
	s_nop 0
	s_nop 0
	s_nop 0
	s_nop 0
	s_nop 0
	s_nop 0
	s_nop 0
	s_nop 0
	s_nop 0
	s_nop 0
	s_mov_b64 s[26:27], 0
